# in-proj GEMM K-loop: LDS-DMA loads with scalar base + 32-bit lane offset (no 64-bit VALU address add per load)
# speedup vs baseline: 1.0198x; 1.0198x over previous
; #define PG8_STAGE(bufoff, gbase, voff) do { _Pragma("unroll") for (int _i = 0; _i < 2; ++_i) \
;         __builtin_amdgcn_global_load_lds((const unsigned*)((const char*)(gbase) + (voff)[_i]), (PG8_LAS unsigned*)(lds + (bufoff) + ldsw + _i * 8192), 16, 0, 0); } while (0)
; #define PG8_LDA(dst, b, h) do { _Pragma("unroll") for (int m = 0; m < 4; ++m) _Pragma("unroll") for (int k = 0; k < 2; ++k) dst[m][k] = *(const PG8_LAS bf16x8*)(lds + PG8_SA(b, h) + aoff + m * 2048 + k * 1024); } while (0)
; #define PG8_LDB(dst, b, h) do { _Pragma("unroll") for (int n = 0; n < 2; ++n) _Pragma("unroll") for (int k = 0; k < 2; ++k) dst[n][k] = *(const PG8_LAS bf16x8*)(lds + PG8_SB(b, h) + boff + n * 2048 + k * 1024); } while (0)
; #define PG8_MMA(ai, bj, At, Bt) do { __builtin_amdgcn_s_setprio(1); _Pragma("unroll") for (int m = 0; m < 4; ++m) _Pragma("unroll") for (int n = 0; n < 2; ++n) _Pragma("unroll") for (int k = 0; k < 2; ++k) \
;         acc[ai][bj][m][n] = __builtin_amdgcn_mfma_f32_16x16x32_bf16(Bt[n][k], At[m][k], acc[ai][bj][m][n], 0, 0, 0); __builtin_amdgcn_s_setprio(0); } while (0)
; #define PG8_WAIT_V(n) asm volatile("s_waitcnt vmcnt(" #n ")" ::: "memory")
; #define PG8_WAIT_L(n) asm volatile("s_waitcnt lgkmcnt(" #n ")" ::: "memory")
; #define PG8_BAR __builtin_amdgcn_s_barrier()
; #define PG8_SCHED __builtin_amdgcn_sched_barrier(0)
; template <class Epi, class Sched, bool ALIGN_EPI = false, bool SP2 = false>
; __device__ __forceinline__ void gemm_phase(PG8_LAS unsigned char* lds, const Gemm g, const Sched& S, const Epi& E) {
;     ...
;             if constexpr (SP2) {
;             PG8_LDB(B0, 0, 0); PG8_LDB(B1, 0, 1); PG8_SCHED; PG8_LDA(At, 0, 0); PG8_STAGE(PG8_SA(1, 1), a1 + hstep, voffA);
;             PG8_WAIT_V(8); PG8_WAIT_L(0); PG8_BAR; PG8_MMA(0, 0, At, B0); PG8_MMA(0, 1, At, B1); PG8_BAR; PG8_SCHED;
;             PG8_LDA(At, 0, 1); PG8_STAGE(PG8_SB(0, 0), b2, voffB); PG8_STAGE(PG8_SB(0, 1), b2 + hstep, voffB); PG8_STAGE(PG8_SA(0, 0), a2, voffA);
;             PG8_WAIT_V(8); PG8_WAIT_L(0); PG8_BAR; PG8_MMA(1, 0, At, B0); PG8_MMA(1, 1, At, B1); PG8_BAR; PG8_SCHED;
.LBB0_214:
	v_add_u32_e32 v134, s88, v177
	v_add_u32_e32 v172, s89, v177
	ds_read_b128 v[114:117], v134
	ds_read_b128 v[118:121], v134 offset:1024
	ds_read_b128 v[130:133], v134 offset:2048
	ds_read_b128 v[134:137], v134 offset:3072
	ds_read_b128 v[146:149], v172
	ds_read_b128 v[150:153], v172 offset:1024
	ds_read_b128 v[168:171], v172 offset:2048
	ds_read_b128 v[172:175], v172 offset:3072
	s_add_u32 s40, s34, 0xfff80080
	s_addc_u32 s41, s35, -1
	s_cmp_eq_u32 s46, 28
	s_cselect_b32 s43, s15, s41
	s_cselect_b32 s42, s19, s40
	s_cselect_b32 s41, s17, s45
	s_cselect_b32 s40, s37, s44
	s_add_i32 m0, s8, 0xc000
	ds_read_b128 v[180:183], v178
	ds_read_b128 v[184:187], v178 offset:1024
	ds_read_b128 v[188:191], v178 offset:2048
	ds_read_b128 v[192:195], v178 offset:3072
	ds_read_b128 v[196:199], v178 offset:4096
	ds_read_b128 v[200:203], v178 offset:5120
	ds_read_b128 v[208:211], v178 offset:6144
	ds_read_b128 v[230:233], v178 offset:7168
	global_load_lds_dwordx4 v164, s[34:35]
	s_add_i32 m0, s8, 0xe000
	s_nop 0
	global_load_lds_dwordx4 v166, s[34:35]
	s_waitcnt vmcnt(8)
	s_waitcnt lgkmcnt(0)
	s_barrier
	s_setprio 1
	s_waitcnt lgkmcnt(0)
	v_mfma_f32_16x16x32_bf16 v[142:145], v[114:117], v[180:183], v[142:145]
	v_mfma_f32_16x16x32_bf16 v[138:141], v[130:133], v[180:183], v[138:141]
	v_mfma_f32_16x16x32_bf16 v[110:113], v[114:117], v[188:191], v[110:113]
	v_mfma_f32_16x16x32_bf16 v[106:109], v[130:133], v[188:191], v[106:109]
	v_mfma_f32_16x16x32_bf16 v[94:97], v[114:117], v[196:199], v[94:97]
	v_mfma_f32_16x16x32_bf16 v[90:93], v[130:133], v[196:199], v[90:93]
	v_mfma_f32_16x16x32_bf16 v[78:81], v[114:117], v[208:211], v[78:81]
	v_mfma_f32_16x16x32_bf16 v[74:77], v[130:133], v[208:211], v[74:77]
	v_mfma_f32_16x16x32_bf16 v[142:145], v[118:121], v[184:187], v[142:145]
	v_mfma_f32_16x16x32_bf16 v[138:141], v[134:137], v[184:187], v[138:141]
	v_mfma_f32_16x16x32_bf16 v[110:113], v[118:121], v[192:195], v[110:113]
	v_mfma_f32_16x16x32_bf16 v[106:109], v[134:137], v[192:195], v[106:109]
	v_mfma_f32_16x16x32_bf16 v[94:97], v[118:121], v[200:203], v[94:97]
	v_mfma_f32_16x16x32_bf16 v[90:93], v[134:137], v[200:203], v[90:93]
	v_mfma_f32_16x16x32_bf16 v[78:81], v[118:121], v[230:233], v[78:81]
	v_mfma_f32_16x16x32_bf16 v[74:77], v[134:137], v[230:233], v[74:77]
	s_setprio 0
	s_setprio 1
	v_mfma_f32_16x16x32_bf16 v[126:129], v[146:149], v[180:183], v[126:129]
	v_mfma_f32_16x16x32_bf16 v[122:125], v[168:171], v[180:183], v[122:125]
	v_mfma_f32_16x16x32_bf16 v[102:105], v[146:149], v[188:191], v[102:105]
	v_mfma_f32_16x16x32_bf16 v[98:101], v[168:171], v[188:191], v[98:101]
	v_mfma_f32_16x16x32_bf16 v[86:89], v[146:149], v[196:199], v[86:89]
	v_mfma_f32_16x16x32_bf16 v[82:85], v[168:171], v[196:199], v[82:85]
	v_mfma_f32_16x16x32_bf16 v[70:73], v[146:149], v[208:211], v[70:73]
	v_mfma_f32_16x16x32_bf16 v[66:69], v[168:171], v[208:211], v[66:69]
	v_mfma_f32_16x16x32_bf16 v[126:129], v[150:153], v[184:187], v[126:129]
	v_mfma_f32_16x16x32_bf16 v[122:125], v[172:175], v[184:187], v[122:125]
	v_mfma_f32_16x16x32_bf16 v[102:105], v[150:153], v[192:195], v[102:105]
	v_mfma_f32_16x16x32_bf16 v[98:101], v[172:175], v[192:195], v[98:101]
	v_mfma_f32_16x16x32_bf16 v[86:89], v[150:153], v[200:203], v[86:89]
	v_mfma_f32_16x16x32_bf16 v[82:85], v[172:175], v[200:203], v[82:85]
	v_mfma_f32_16x16x32_bf16 v[70:73], v[150:153], v[230:233], v[70:73]
	v_mfma_f32_16x16x32_bf16 v[66:69], v[172:175], v[230:233], v[66:69]
	s_setprio 0
	s_barrier
	s_add_i32 s47, s88, s6
	s_mov_b32 m0, s47
	ds_read_b128 v[180:183], v178 offset:16384
	ds_read_b128 v[184:187], v178 offset:17408
	ds_read_b128 v[188:191], v178 offset:18432
	ds_read_b128 v[192:195], v178 offset:19456
	ds_read_b128 v[196:199], v178 offset:20480
	ds_read_b128 v[200:203], v178 offset:21504
	ds_read_b128 v[208:211], v178 offset:22528
	ds_read_b128 v[230:233], v178 offset:23552
	global_load_lds_dwordx4 v0, s[40:41]
	s_add_i32 m0, s47, 0x2000
	s_add_u32 s50, s40, 0x80000
	s_addc_u32 s51, s41, 0
	s_add_i32 s47, s89, s6
	global_load_lds_dwordx4 v154, s[40:41]
	s_mov_b32 m0, s47
	s_nop 0
	global_load_lds_dwordx4 v0, s[50:51]
	s_add_i32 m0, s47, 0x2000
	s_nop 0
	global_load_lds_dwordx4 v154, s[50:51]
	s_mov_b32 m0, s8
	s_nop 0
	global_load_lds_dwordx4 v158, s[42:43]
	s_mov_b32 m0, s9
	s_nop 0
	global_load_lds_dwordx4 v156, s[42:43]
	s_waitcnt vmcnt(8)
	s_waitcnt lgkmcnt(0)
	s_barrier
	s_setprio 1
	s_waitcnt lgkmcnt(0)
	v_mfma_f32_16x16x32_bf16 v[62:65], v[114:117], v[180:183], v[62:65]
	v_mfma_f32_16x16x32_bf16 v[58:61], v[130:133], v[180:183], v[58:61]
	v_mfma_f32_16x16x32_bf16 v[46:49], v[114:117], v[188:191], v[46:49]
	v_mfma_f32_16x16x32_bf16 v[42:45], v[130:133], v[188:191], v[42:45]
	v_mfma_f32_16x16x32_bf16 v[30:33], v[114:117], v[196:199], v[30:33]
	v_mfma_f32_16x16x32_bf16 v[26:29], v[130:133], v[196:199], v[26:29]
	v_mfma_f32_16x16x32_bf16 v[14:17], v[114:117], v[208:211], v[14:17]
	v_mfma_f32_16x16x32_bf16 v[10:13], v[130:133], v[208:211], v[10:13]
	v_mfma_f32_16x16x32_bf16 v[62:65], v[118:121], v[184:187], v[62:65]
	v_mfma_f32_16x16x32_bf16 v[58:61], v[134:137], v[184:187], v[58:61]
	v_mfma_f32_16x16x32_bf16 v[46:49], v[118:121], v[192:195], v[46:49]
	v_mfma_f32_16x16x32_bf16 v[42:45], v[134:137], v[192:195], v[42:45]
	v_mfma_f32_16x16x32_bf16 v[30:33], v[118:121], v[200:203], v[30:33]
	v_mfma_f32_16x16x32_bf16 v[26:29], v[134:137], v[200:203], v[26:29]
	v_mfma_f32_16x16x32_bf16 v[14:17], v[118:121], v[230:233], v[14:17]
	v_mfma_f32_16x16x32_bf16 v[10:13], v[134:137], v[230:233], v[10:13]
	s_setprio 0
	s_setprio 1
	v_mfma_f32_16x16x32_bf16 v[54:57], v[146:149], v[180:183], v[54:57]
	v_mfma_f32_16x16x32_bf16 v[50:53], v[168:171], v[180:183], v[50:53]
	v_mfma_f32_16x16x32_bf16 v[38:41], v[146:149], v[188:191], v[38:41]
	v_mfma_f32_16x16x32_bf16 v[34:37], v[168:171], v[188:191], v[34:37]
	v_mfma_f32_16x16x32_bf16 v[22:25], v[146:149], v[196:199], v[22:25]
	v_mfma_f32_16x16x32_bf16 v[18:21], v[168:171], v[196:199], v[18:21]
	v_mfma_f32_16x16x32_bf16 v[6:9], v[146:149], v[208:211], v[6:9]
	v_mfma_f32_16x16x32_bf16 v[2:5], v[168:171], v[208:211], v[2:5]
	v_mfma_f32_16x16x32_bf16 v[54:57], v[150:153], v[184:187], v[54:57]
	v_mfma_f32_16x16x32_bf16 v[50:53], v[172:175], v[184:187], v[50:53]
	v_mfma_f32_16x16x32_bf16 v[38:41], v[150:153], v[192:195], v[38:41]
	v_mfma_f32_16x16x32_bf16 v[34:37], v[172:175], v[192:195], v[34:37]
	v_mfma_f32_16x16x32_bf16 v[22:25], v[150:153], v[200:203], v[22:25]
	v_mfma_f32_16x16x32_bf16 v[18:21], v[172:175], v[200:203], v[18:21]
	v_mfma_f32_16x16x32_bf16 v[6:9], v[150:153], v[230:233], v[6:9]
	v_mfma_f32_16x16x32_bf16 v[2:5], v[172:175], v[230:233], v[2:5]
	s_setprio 0
	s_barrier
; #define PG8_STAGE(bufoff, gbase, voff) do { _Pragma("unroll") for (int _i = 0; _i < 2; ++_i) \
;         __builtin_amdgcn_global_load_lds((const unsigned*)((const char*)(gbase) + (voff)[_i]), (PG8_LAS unsigned*)(lds + (bufoff) + ldsw + _i * 8192), 16, 0, 0); } while (0)
; #define PG8_LDA(dst, b, h) do { _Pragma("unroll") for (int m = 0; m < 4; ++m) _Pragma("unroll") for (int k = 0; k < 2; ++k) dst[m][k] = *(const PG8_LAS bf16x8*)(lds + PG8_SA(b, h) + aoff + m * 2048 + k * 1024); } while (0)
; #define PG8_LDB(dst, b, h) do { _Pragma("unroll") for (int n = 0; n < 2; ++n) _Pragma("unroll") for (int k = 0; k < 2; ++k) dst[n][k] = *(const PG8_LAS bf16x8*)(lds + PG8_SB(b, h) + boff + n * 2048 + k * 1024); } while (0)
; #define PG8_MMA(ai, bj, At, Bt) do { __builtin_amdgcn_s_setprio(1); _Pragma("unroll") for (int m = 0; m < 4; ++m) _Pragma("unroll") for (int n = 0; n < 2; ++n) _Pragma("unroll") for (int k = 0; k < 2; ++k) \
;         acc[ai][bj][m][n] = __builtin_amdgcn_mfma_f32_16x16x32_bf16(Bt[n][k], At[m][k], acc[ai][bj][m][n], 0, 0, 0); __builtin_amdgcn_s_setprio(0); } while (0)
; #define PG8_WAIT_V(n) asm volatile("s_waitcnt vmcnt(" #n ")" ::: "memory")
; #define PG8_WAIT_L(n) asm volatile("s_waitcnt lgkmcnt(" #n ")" ::: "memory")
; #define PG8_BAR __builtin_amdgcn_s_barrier()
; #define PG8_SCHED __builtin_amdgcn_sched_barrier(0)
; template <class Epi, class Sched, bool ALIGN_EPI = false, bool SP2 = false>
; __device__ __forceinline__ void gemm_phase(PG8_LAS unsigned char* lds, const Gemm g, const Sched& S, const Epi& E) {
;     ...
;         for (int t = 0; t < nt; t += 2) {
;             const bool last = (t == nt - 2);
;             const char* a1 = cA + (size_t)(t + 1) * kstep;
;             const char* a2 = last ? nA : cA + (size_t)(t + 2) * kstep; const char* b2 = last ? nB : cB + (size_t)(t + 2) * kstep;
;     ...
;             PG8_LDB(B0, 1, 0); PG8_LDB(B1, 1, 1); PG8_SCHED; PG8_LDA(At, 1, 0); PG8_STAGE(PG8_SA(0, 1), a2 + hstep, voffA);
;             PG8_WAIT_V(8); PG8_WAIT_L(0); PG8_BAR; PG8_MMA(0, 0, At, B0); PG8_MMA(0, 1, At, B1); PG8_BAR; PG8_SCHED;
;             PG8_LDA(At, 1, 1); PG8_STAGE(PG8_SB(1, 0), b3, voffB); PG8_STAGE(PG8_SB(1, 1), b3 + hstep, voffB); PG8_STAGE(PG8_SA(1, 0), a3, voffA);
;             PG8_WAIT_V(8); PG8_WAIT_L(0); PG8_BAR; PG8_MMA(1, 0, At, B0); PG8_MMA(1, 1, At, B1); PG8_BAR; PG8_SCHED;
	s_add_i32 s47, 0, 0x1c000
	v_add_u32_e32 v134, s90, v177
	v_add_u32_e32 v172, s47, v177
	ds_read_b128 v[114:117], v134
	ds_read_b128 v[118:121], v134 offset:1024
	ds_read_b128 v[130:133], v134 offset:2048
	ds_read_b128 v[134:137], v134 offset:3072
	ds_read_b128 v[146:149], v172
	ds_read_b128 v[150:153], v172 offset:1024
	ds_read_b128 v[168:171], v172 offset:2048
	ds_read_b128 v[172:175], v172 offset:3072
	s_add_u32 s50, s42, 0x80000
	s_addc_u32 s51, s43, 0
	s_mov_b32 m0, s10
	ds_read_b128 v[180:183], v178 offset:32768
	ds_read_b128 v[184:187], v178 offset:33792
	ds_read_b128 v[188:191], v178 offset:34816
	ds_read_b128 v[192:195], v178 offset:35840
	ds_read_b128 v[196:199], v178 offset:36864
	ds_read_b128 v[200:203], v178 offset:37888
	ds_read_b128 v[208:211], v178 offset:38912
	ds_read_b128 v[230:233], v178 offset:39936
	global_load_lds_dwordx4 v158, s[50:51]
	s_mov_b32 m0, s11
	s_nop 0
	global_load_lds_dwordx4 v156, s[50:51]
	s_waitcnt vmcnt(8)
	s_waitcnt lgkmcnt(0)
	s_barrier
	s_setprio 1
	s_waitcnt lgkmcnt(0)
	v_mfma_f32_16x16x32_bf16 v[142:145], v[114:117], v[180:183], v[142:145]
	v_mfma_f32_16x16x32_bf16 v[138:141], v[130:133], v[180:183], v[138:141]
	v_mfma_f32_16x16x32_bf16 v[110:113], v[114:117], v[188:191], v[110:113]
	v_mfma_f32_16x16x32_bf16 v[106:109], v[130:133], v[188:191], v[106:109]
	v_mfma_f32_16x16x32_bf16 v[94:97], v[114:117], v[196:199], v[94:97]
	v_mfma_f32_16x16x32_bf16 v[90:93], v[130:133], v[196:199], v[90:93]
	v_mfma_f32_16x16x32_bf16 v[78:81], v[114:117], v[208:211], v[78:81]
	v_mfma_f32_16x16x32_bf16 v[74:77], v[130:133], v[208:211], v[74:77]
	v_mfma_f32_16x16x32_bf16 v[142:145], v[118:121], v[184:187], v[142:145]
	v_mfma_f32_16x16x32_bf16 v[138:141], v[134:137], v[184:187], v[138:141]
	v_mfma_f32_16x16x32_bf16 v[110:113], v[118:121], v[192:195], v[110:113]
	v_mfma_f32_16x16x32_bf16 v[106:109], v[134:137], v[192:195], v[106:109]
	v_mfma_f32_16x16x32_bf16 v[94:97], v[118:121], v[200:203], v[94:97]
	v_mfma_f32_16x16x32_bf16 v[90:93], v[134:137], v[200:203], v[90:93]
	v_mfma_f32_16x16x32_bf16 v[78:81], v[118:121], v[230:233], v[78:81]
	v_mfma_f32_16x16x32_bf16 v[74:77], v[134:137], v[230:233], v[74:77]
	s_setprio 0
	s_setprio 1
	v_mfma_f32_16x16x32_bf16 v[126:129], v[146:149], v[180:183], v[126:129]
	v_mfma_f32_16x16x32_bf16 v[122:125], v[168:171], v[180:183], v[122:125]
	v_mfma_f32_16x16x32_bf16 v[102:105], v[146:149], v[188:191], v[102:105]
	v_mfma_f32_16x16x32_bf16 v[98:101], v[168:171], v[188:191], v[98:101]
	v_mfma_f32_16x16x32_bf16 v[86:89], v[146:149], v[196:199], v[86:89]
	v_mfma_f32_16x16x32_bf16 v[82:85], v[168:171], v[196:199], v[82:85]
	v_mfma_f32_16x16x32_bf16 v[70:73], v[146:149], v[208:211], v[70:73]
	v_mfma_f32_16x16x32_bf16 v[66:69], v[168:171], v[208:211], v[66:69]
	v_mfma_f32_16x16x32_bf16 v[126:129], v[150:153], v[184:187], v[126:129]
	v_mfma_f32_16x16x32_bf16 v[122:125], v[172:175], v[184:187], v[122:125]
	v_mfma_f32_16x16x32_bf16 v[102:105], v[150:153], v[192:195], v[102:105]
	v_mfma_f32_16x16x32_bf16 v[98:101], v[172:175], v[192:195], v[98:101]
	v_mfma_f32_16x16x32_bf16 v[86:89], v[150:153], v[200:203], v[86:89]
	v_mfma_f32_16x16x32_bf16 v[82:85], v[172:175], v[200:203], v[82:85]
	v_mfma_f32_16x16x32_bf16 v[70:73], v[150:153], v[230:233], v[70:73]
	v_mfma_f32_16x16x32_bf16 v[66:69], v[172:175], v[230:233], v[66:69]
	s_setprio 0
	s_barrier
	s_add_i32 vcc_lo, s90, s6
	s_add_u32 s50, s40, 0x80
	s_addc_u32 s51, s41, 0
	s_mov_b32 m0, vcc_lo
	ds_read_b128 v[180:183], v178 offset:49152
	ds_read_b128 v[184:187], v178 offset:50176
	ds_read_b128 v[188:191], v178 offset:51200
	ds_read_b128 v[192:195], v178 offset:52224
	ds_read_b128 v[196:199], v178 offset:53248
	ds_read_b128 v[200:203], v178 offset:54272
	ds_read_b128 v[208:211], v178 offset:55296
	ds_read_b128 v[230:233], v178 offset:56320
	global_load_lds_dwordx4 v0, s[50:51]
	s_add_i32 m0, vcc_lo, 0x2000
	s_add_i32 vcc_lo, s47, s6
	global_load_lds_dwordx4 v154, s[50:51]
	s_add_u32 s40, s40, 0x80080
	s_addc_u32 s41, s41, 0
	s_mov_b32 m0, vcc_lo
	s_nop 0
	global_load_lds_dwordx4 v0, s[40:41]
	s_add_i32 m0, vcc_lo, 0x2000
	s_nop 0
	global_load_lds_dwordx4 v154, s[40:41]
	s_add_u32 s50, s42, 0x80
	s_addc_u32 s51, s43, 0
	s_mov_b32 m0, s13
	s_nop 0
	global_load_lds_dwordx4 v158, s[50:51]
	s_mov_b32 m0, s25
	s_nop 0
	global_load_lds_dwordx4 v156, s[50:51]
	s_waitcnt vmcnt(8)
	s_waitcnt lgkmcnt(0)
	s_barrier
	s_setprio 1
	s_waitcnt lgkmcnt(0)
	v_mfma_f32_16x16x32_bf16 v[62:65], v[114:117], v[180:183], v[62:65]
	v_mfma_f32_16x16x32_bf16 v[58:61], v[130:133], v[180:183], v[58:61]
	v_mfma_f32_16x16x32_bf16 v[46:49], v[114:117], v[188:191], v[46:49]
	v_mfma_f32_16x16x32_bf16 v[42:45], v[130:133], v[188:191], v[42:45]
	v_mfma_f32_16x16x32_bf16 v[30:33], v[114:117], v[196:199], v[30:33]
	v_mfma_f32_16x16x32_bf16 v[26:29], v[130:133], v[196:199], v[26:29]
	v_mfma_f32_16x16x32_bf16 v[14:17], v[114:117], v[208:211], v[14:17]
	v_mfma_f32_16x16x32_bf16 v[10:13], v[130:133], v[208:211], v[10:13]
	v_mfma_f32_16x16x32_bf16 v[62:65], v[118:121], v[184:187], v[62:65]
	v_mfma_f32_16x16x32_bf16 v[58:61], v[134:137], v[184:187], v[58:61]
	v_mfma_f32_16x16x32_bf16 v[46:49], v[118:121], v[192:195], v[46:49]
	v_mfma_f32_16x16x32_bf16 v[42:45], v[134:137], v[192:195], v[42:45]
	v_mfma_f32_16x16x32_bf16 v[30:33], v[118:121], v[200:203], v[30:33]
	v_mfma_f32_16x16x32_bf16 v[26:29], v[134:137], v[200:203], v[26:29]
	v_mfma_f32_16x16x32_bf16 v[14:17], v[118:121], v[230:233], v[14:17]
	v_mfma_f32_16x16x32_bf16 v[10:13], v[134:137], v[230:233], v[10:13]
	s_setprio 0
	s_setprio 1
	v_mfma_f32_16x16x32_bf16 v[54:57], v[146:149], v[180:183], v[54:57]
	v_mfma_f32_16x16x32_bf16 v[50:53], v[168:171], v[180:183], v[50:53]
	v_mfma_f32_16x16x32_bf16 v[38:41], v[146:149], v[188:191], v[38:41]
	v_mfma_f32_16x16x32_bf16 v[34:37], v[168:171], v[188:191], v[34:37]
	v_mfma_f32_16x16x32_bf16 v[22:25], v[146:149], v[196:199], v[22:25]
	v_mfma_f32_16x16x32_bf16 v[18:21], v[168:171], v[196:199], v[18:21]
	v_mfma_f32_16x16x32_bf16 v[6:9], v[146:149], v[208:211], v[6:9]
	v_mfma_f32_16x16x32_bf16 v[2:5], v[168:171], v[208:211], v[2:5]
	v_mfma_f32_16x16x32_bf16 v[54:57], v[150:153], v[184:187], v[54:57]
	v_mfma_f32_16x16x32_bf16 v[50:53], v[172:175], v[184:187], v[50:53]
	v_mfma_f32_16x16x32_bf16 v[38:41], v[150:153], v[192:195], v[38:41]
	v_mfma_f32_16x16x32_bf16 v[34:37], v[172:175], v[192:195], v[34:37]
	v_mfma_f32_16x16x32_bf16 v[22:25], v[150:153], v[200:203], v[22:25]
	v_mfma_f32_16x16x32_bf16 v[18:21], v[172:175], v[200:203], v[18:21]
	v_mfma_f32_16x16x32_bf16 v[6:9], v[150:153], v[230:233], v[6:9]
	v_mfma_f32_16x16x32_bf16 v[2:5], v[172:175], v[230:233], v[2:5]
	s_setprio 0
	s_barrier
	s_add_i32 s46, s46, 2
	s_add_u32 s34, s34, 0x100
	s_addc_u32 s35, s35, 0
	s_add_u32 s44, s44, 0x100
	s_addc_u32 s45, s45, 0
	s_cmp_gt_u32 s46, 29
	s_cbranch_scc0 .LBB0_214
	s_and_b64 vcc, exec, s[2:3]
	s_cbranch_vccz .LBB0_217
	s_barrier
